# AP1: prologue adaLN partials GEMV: rolling prefetch (each row load for the next iteration issued right after its FMA group, 8 loads always in flight); on top of BE1
# baseline (speedup 1.0000x reference)
.LBB0_21:
	s_ashr_i32 s4, s39, 3
	s_mul_hi_i32 s5, s4, 0x2aaaaaab
	s_lshr_b32 s6, s5, 31
	s_lshr_b32 s5, s5, 3
	s_add_i32 s5, s5, s6
	s_mul_i32 s5, s5, 48
	s_sub_i32 s4, s4, s5
	s_mul_hi_i32 s5, s39, 0x2aaaaaab
	s_lshr_b32 s6, s5, 31
	s_ashr_i32 s41, s5, 6
	s_lshl_b32 s4, s4, 8
	s_add_i32 s41, s41, s6
	s_ashr_i32 s5, s4, 31
	s_mul_i32 s43, s41, 0x6000000
	s_lshl_b64 s[6:7], s[4:5], 2
	s_mul_hi_i32 s42, s41, 0x6000000
	s_add_u32 s6, s43, s6
	s_addc_u32 s7, s42, s7
	v_lshl_add_u64 v[46:47], v[44:45], 0, s[6:7]
	s_mov_b64 s[6:7], 0
	s_mov_b32 s42, s1
	v_mov_b32_e32 v6, 0
	v_mov_b32_e32 v7, v41
	v_mov_b32_e32 v8, 0
	v_mov_b32_e32 v9, v41
	v_mov_b32_e32 v10, 0
	v_mov_b32_e32 v11, v41
	v_mov_b32_e32 v12, 0
	v_mov_b32_e32 v13, v41
	v_mov_b32_e32 v14, 0
	v_mov_b32_e32 v15, v41
	v_mov_b32_e32 v16, 0
	v_mov_b32_e32 v17, v41
	v_mov_b32_e32 v2, 0
	v_mov_b32_e32 v3, v41
	v_mov_b32_e32 v4, 0
	v_mov_b32_e32 v5, v41
	v_mov_b32_e32 v18, 0
	v_mov_b32_e32 v19, v41
	v_mov_b32_e32 v20, 0
	v_mov_b32_e32 v21, v41
	v_mov_b32_e32 v26, 0
	v_mov_b32_e32 v27, v41
	v_mov_b32_e32 v28, 0
	v_mov_b32_e32 v29, v41
	v_mov_b32_e32 v34, 0
	v_mov_b32_e32 v35, v41
	v_mov_b32_e32 v36, 0
	v_mov_b32_e32 v37, v41
	v_mov_b32_e32 v22, 0
	v_mov_b32_e32 v23, v41
	v_mov_b32_e32 v24, 0
	v_mov_b32_e32 v25, v41
	v_mov_b32_e32 v30, 0
	v_mov_b32_e32 v31, v41
	v_mov_b32_e32 v32, 0
	v_mov_b32_e32 v33, v41
	s_mov_b32 s100, 0
	s_mov_b32 s101, 0
	v_lshl_add_u64 v[50:51], v[46:47], 0, s[100:101]
	s_add_u32 s100, s100, 0xc000
	global_load_dwordx4 v[50:53], v[50:51], off
	s_nop 0
	v_lshl_add_u64 v[118:119], v[46:47], 0, s[100:101]
	s_add_u32 s100, s100, 0xc000
	global_load_dwordx4 v[118:121], v[118:119], off
	s_nop 0
	v_lshl_add_u64 v[122:123], v[46:47], 0, s[100:101]
	s_add_u32 s100, s100, 0xc000
	global_load_dwordx4 v[122:125], v[122:123], off
	s_nop 0
	v_lshl_add_u64 v[126:127], v[46:47], 0, s[100:101]
	s_add_u32 s100, s100, 0xc000
	global_load_dwordx4 v[126:129], v[126:127], off
	s_nop 0
	v_lshl_add_u64 v[130:131], v[46:47], 0, s[100:101]
	s_add_u32 s100, s100, 0xc000
	global_load_dwordx4 v[130:133], v[130:131], off
	s_nop 0
	v_lshl_add_u64 v[134:135], v[46:47], 0, s[100:101]
	s_add_u32 s100, s100, 0xc000
	global_load_dwordx4 v[134:137], v[134:135], off
	s_nop 0
	v_lshl_add_u64 v[138:139], v[46:47], 0, s[100:101]
	s_add_u32 s100, s100, 0xc000
	global_load_dwordx4 v[138:141], v[138:139], off
	s_nop 0
	v_lshl_add_u64 v[142:143], v[46:47], 0, s[100:101]
	s_add_u32 s100, s100, 0xc000
	global_load_dwordx4 v[142:145], v[142:143], off
	s_nop 0
.LBB0_22:
	v_mov_b32_e32 v40, s42
	ds_read_b128 v[54:57], v40
	ds_read_b128 v[58:61], v40 offset:16
	ds_read2_b32 v[146:147], v40 offset0:8 offset1:20
	ds_read_b128 v[62:65], v40 offset:48
	ds_read_b128 v[66:69], v40 offset:64
	ds_read_b128 v[70:73], v40 offset:96
	ds_read_b128 v[74:77], v40 offset:112
	ds_read2_b32 v[148:149], v40 offset0:32 offset1:44
	ds_read_b128 v[78:81], v40 offset:144
	ds_read_b128 v[82:85], v40 offset:160
	ds_read_b128 v[86:89], v40 offset:192
	ds_read_b128 v[90:93], v40 offset:208
	ds_read2_b32 v[150:151], v40 offset0:56 offset1:68
	ds_read_b128 v[94:97], v40 offset:240
	ds_read_b128 v[98:101], v40 offset:256
	ds_read_b128 v[102:105], v40 offset:288
	ds_read_b128 v[106:109], v40 offset:304
	ds_read2_b32 v[152:153], v40 offset0:80 offset1:92
	ds_read_b128 v[110:113], v40 offset:336
	ds_read_b128 v[114:117], v40 offset:352
	s_waitcnt lgkmcnt(14)
	v_mov_b32_e32 v40, v57
	v_mov_b32_e32 v48, v61
	v_mov_b32_e32 v154, v65
	v_mov_b32_e32 v156, v69
	v_mov_b32_e32 v158, v147
	v_mov_b32_e32 v160, v73
	s_waitcnt lgkmcnt(13)
	v_mov_b32_e32 v162, v77
	s_waitcnt lgkmcnt(11)
	v_mov_b32_e32 v164, v81
	s_waitcnt lgkmcnt(10)
	v_mov_b32_e32 v166, v85
	v_mov_b32_e32 v168, v149
	s_waitcnt lgkmcnt(9)
	v_mov_b32_e32 v170, v89
	s_waitcnt lgkmcnt(8)
	v_mov_b32_e32 v172, v93
	s_addk_i32 s42, 0x180
	s_waitcnt lgkmcnt(6)
	v_mov_b32_e32 v174, v97
	s_waitcnt lgkmcnt(5)
	v_mov_b32_e32 v176, v101
	v_mov_b32_e32 v178, v151
	s_add_u32 s6, s6, 0x60000
	s_waitcnt lgkmcnt(4)
	v_mov_b32_e32 v180, v105
	s_waitcnt lgkmcnt(3)
	v_mov_b32_e32 v182, v109
	s_addc_u32 s7, s7, 0
	s_waitcnt lgkmcnt(1)
	v_mov_b32_e32 v184, v113
	s_waitcnt lgkmcnt(0)
	v_mov_b32_e32 v186, v117
	v_mov_b32_e32 v188, v153
	s_cmp_eq_u32 s6, 0xc00000
	s_cselect_b32 s100, 0xba0000, s6
	s_mov_b32 s101, 0
	s_waitcnt vmcnt(7)
	v_pk_fma_f32 v[8:9], v[52:53], v[54:55], v[8:9] op_sel_hi:[1,0,1]
	v_pk_fma_f32 v[6:7], v[50:51], v[54:55], v[6:7] op_sel_hi:[1,0,1]
	v_pk_fma_f32 v[12:13], v[52:53], v[54:55], v[12:13] op_sel:[0,1,0]
	v_pk_fma_f32 v[10:11], v[50:51], v[54:55], v[10:11] op_sel:[0,1,0]
	v_pk_fma_f32 v[14:15], v[50:51], v[56:57], v[14:15] op_sel_hi:[1,0,1]
	v_pk_fma_f32 v[16:17], v[52:53], v[56:57], v[16:17] op_sel_hi:[1,0,1]
	v_pk_fma_f32 v[20:21], v[52:53], v[58:59], v[20:21] op_sel_hi:[1,0,1]
	v_pk_fma_f32 v[18:19], v[50:51], v[58:59], v[18:19] op_sel_hi:[1,0,1]
	v_pk_fma_f32 v[28:29], v[52:53], v[58:59], v[28:29] op_sel:[0,1,0]
	v_pk_fma_f32 v[26:27], v[50:51], v[58:59], v[26:27] op_sel:[0,1,0]
	v_pk_fma_f32 v[34:35], v[50:51], v[60:61], v[34:35] op_sel_hi:[1,0,1]
	v_pk_fma_f32 v[36:37], v[52:53], v[60:61], v[36:37] op_sel_hi:[1,0,1]
	v_pk_fma_f32 v[2:3], v[50:51], v[40:41], v[2:3] op_sel_hi:[1,0,1]
	v_pk_fma_f32 v[4:5], v[52:53], v[40:41], v[4:5] op_sel_hi:[1,0,1]
	v_pk_fma_f32 v[22:23], v[50:51], v[48:49], v[22:23] op_sel_hi:[1,0,1]
	v_pk_fma_f32 v[24:25], v[52:53], v[48:49], v[24:25] op_sel_hi:[1,0,1]
	v_pk_fma_f32 v[30:31], v[50:51], v[146:147], v[30:31] op_sel_hi:[1,0,1]
	v_pk_fma_f32 v[32:33], v[52:53], v[146:147], v[32:33] op_sel_hi:[1,0,1]
	v_lshl_add_u64 v[50:51], v[46:47], 0, s[100:101]
	s_add_u32 s100, s100, 0xc000
	global_load_dwordx4 v[50:53], v[50:51], off
	s_nop 0
	s_waitcnt vmcnt(7)
	v_pk_fma_f32 v[6:7], v[118:119], v[62:63], v[6:7] op_sel_hi:[1,0,1]
	v_pk_fma_f32 v[8:9], v[120:121], v[62:63], v[8:9] op_sel_hi:[1,0,1]
	v_pk_fma_f32 v[10:11], v[118:119], v[62:63], v[10:11] op_sel:[0,1,0]
	v_pk_fma_f32 v[12:13], v[120:121], v[62:63], v[12:13] op_sel:[0,1,0]
	v_pk_fma_f32 v[14:15], v[118:119], v[64:65], v[14:15] op_sel_hi:[1,0,1]
	v_pk_fma_f32 v[16:17], v[120:121], v[64:65], v[16:17] op_sel_hi:[1,0,1]
	v_pk_fma_f32 v[18:19], v[118:119], v[66:67], v[18:19] op_sel_hi:[1,0,1]
	v_pk_fma_f32 v[20:21], v[120:121], v[66:67], v[20:21] op_sel_hi:[1,0,1]
	v_pk_fma_f32 v[26:27], v[118:119], v[66:67], v[26:27] op_sel:[0,1,0]
	v_pk_fma_f32 v[28:29], v[120:121], v[66:67], v[28:29] op_sel:[0,1,0]
	v_pk_fma_f32 v[34:35], v[118:119], v[68:69], v[34:35] op_sel_hi:[1,0,1]
	v_pk_fma_f32 v[36:37], v[120:121], v[68:69], v[36:37] op_sel_hi:[1,0,1]
	v_pk_fma_f32 v[2:3], v[118:119], v[154:155], v[2:3] op_sel_hi:[1,0,1]
	v_pk_fma_f32 v[4:5], v[120:121], v[154:155], v[4:5] op_sel_hi:[1,0,1]
	v_pk_fma_f32 v[22:23], v[118:119], v[156:157], v[22:23] op_sel_hi:[1,0,1]
	v_pk_fma_f32 v[24:25], v[120:121], v[156:157], v[24:25] op_sel_hi:[1,0,1]
	v_pk_fma_f32 v[30:31], v[118:119], v[158:159], v[30:31] op_sel_hi:[1,0,1]
	v_pk_fma_f32 v[32:33], v[120:121], v[158:159], v[32:33] op_sel_hi:[1,0,1]
	v_lshl_add_u64 v[118:119], v[46:47], 0, s[100:101]
	s_add_u32 s100, s100, 0xc000
	global_load_dwordx4 v[118:121], v[118:119], off
	s_nop 0
	s_waitcnt vmcnt(7)
	v_pk_fma_f32 v[8:9], v[124:125], v[70:71], v[8:9] op_sel_hi:[1,0,1]
	v_pk_fma_f32 v[6:7], v[122:123], v[70:71], v[6:7] op_sel_hi:[1,0,1]
	v_pk_fma_f32 v[12:13], v[124:125], v[70:71], v[12:13] op_sel:[0,1,0]
	v_pk_fma_f32 v[10:11], v[122:123], v[70:71], v[10:11] op_sel:[0,1,0]
	v_pk_fma_f32 v[16:17], v[124:125], v[72:73], v[16:17] op_sel_hi:[1,0,1]
	v_pk_fma_f32 v[14:15], v[122:123], v[72:73], v[14:15] op_sel_hi:[1,0,1]
	v_pk_fma_f32 v[4:5], v[124:125], v[160:161], v[4:5] op_sel_hi:[1,0,1]
	v_pk_fma_f32 v[2:3], v[122:123], v[160:161], v[2:3] op_sel_hi:[1,0,1]
	v_pk_fma_f32 v[20:21], v[124:125], v[74:75], v[20:21] op_sel_hi:[1,0,1]
	v_pk_fma_f32 v[18:19], v[122:123], v[74:75], v[18:19] op_sel_hi:[1,0,1]
	v_pk_fma_f32 v[28:29], v[124:125], v[74:75], v[28:29] op_sel:[0,1,0]
	v_pk_fma_f32 v[26:27], v[122:123], v[74:75], v[26:27] op_sel:[0,1,0]
	v_pk_fma_f32 v[36:37], v[124:125], v[76:77], v[36:37] op_sel_hi:[1,0,1]
	v_pk_fma_f32 v[34:35], v[122:123], v[76:77], v[34:35] op_sel_hi:[1,0,1]
	v_pk_fma_f32 v[24:25], v[124:125], v[162:163], v[24:25] op_sel_hi:[1,0,1]
	v_pk_fma_f32 v[22:23], v[122:123], v[162:163], v[22:23] op_sel_hi:[1,0,1]
	v_pk_fma_f32 v[32:33], v[124:125], v[148:149], v[32:33] op_sel_hi:[1,0,1]
	v_pk_fma_f32 v[30:31], v[122:123], v[148:149], v[30:31] op_sel_hi:[1,0,1]
	v_lshl_add_u64 v[122:123], v[46:47], 0, s[100:101]
	s_add_u32 s100, s100, 0xc000
	global_load_dwordx4 v[122:125], v[122:123], off
	s_nop 0
	s_waitcnt vmcnt(7)
	v_pk_fma_f32 v[8:9], v[128:129], v[78:79], v[8:9] op_sel_hi:[1,0,1]
	v_pk_fma_f32 v[6:7], v[126:127], v[78:79], v[6:7] op_sel_hi:[1,0,1]
	v_pk_fma_f32 v[12:13], v[128:129], v[78:79], v[12:13] op_sel:[0,1,0]
	v_pk_fma_f32 v[10:11], v[126:127], v[78:79], v[10:11] op_sel:[0,1,0]
	v_pk_fma_f32 v[16:17], v[128:129], v[80:81], v[16:17] op_sel_hi:[1,0,1]
	v_pk_fma_f32 v[14:15], v[126:127], v[80:81], v[14:15] op_sel_hi:[1,0,1]
	v_pk_fma_f32 v[20:21], v[128:129], v[82:83], v[20:21] op_sel_hi:[1,0,1]
	v_pk_fma_f32 v[18:19], v[126:127], v[82:83], v[18:19] op_sel_hi:[1,0,1]
	v_pk_fma_f32 v[28:29], v[128:129], v[82:83], v[28:29] op_sel:[0,1,0]
	v_pk_fma_f32 v[26:27], v[126:127], v[82:83], v[26:27] op_sel:[0,1,0]
	v_pk_fma_f32 v[36:37], v[128:129], v[84:85], v[36:37] op_sel_hi:[1,0,1]
	v_pk_fma_f32 v[34:35], v[126:127], v[84:85], v[34:35] op_sel_hi:[1,0,1]
	v_pk_fma_f32 v[4:5], v[128:129], v[164:165], v[4:5] op_sel_hi:[1,0,1]
	v_pk_fma_f32 v[2:3], v[126:127], v[164:165], v[2:3] op_sel_hi:[1,0,1]
	v_pk_fma_f32 v[24:25], v[128:129], v[166:167], v[24:25] op_sel_hi:[1,0,1]
	v_pk_fma_f32 v[22:23], v[126:127], v[166:167], v[22:23] op_sel_hi:[1,0,1]
	v_pk_fma_f32 v[32:33], v[128:129], v[168:169], v[32:33] op_sel_hi:[1,0,1]
	v_pk_fma_f32 v[30:31], v[126:127], v[168:169], v[30:31] op_sel_hi:[1,0,1]
	v_lshl_add_u64 v[126:127], v[46:47], 0, s[100:101]
	s_add_u32 s100, s100, 0xc000
	global_load_dwordx4 v[126:129], v[126:127], off
	s_nop 0
	s_waitcnt vmcnt(7)
	v_pk_fma_f32 v[8:9], v[132:133], v[86:87], v[8:9] op_sel_hi:[1,0,1]
	v_pk_fma_f32 v[6:7], v[130:131], v[86:87], v[6:7] op_sel_hi:[1,0,1]
	v_pk_fma_f32 v[12:13], v[132:133], v[86:87], v[12:13] op_sel:[0,1,0]
	v_pk_fma_f32 v[10:11], v[130:131], v[86:87], v[10:11] op_sel:[0,1,0]
	v_pk_fma_f32 v[16:17], v[132:133], v[88:89], v[16:17] op_sel_hi:[1,0,1]
	v_pk_fma_f32 v[14:15], v[130:131], v[88:89], v[14:15] op_sel_hi:[1,0,1]
	v_pk_fma_f32 v[20:21], v[132:133], v[90:91], v[20:21] op_sel_hi:[1,0,1]
	v_pk_fma_f32 v[18:19], v[130:131], v[90:91], v[18:19] op_sel_hi:[1,0,1]
	v_pk_fma_f32 v[28:29], v[132:133], v[90:91], v[28:29] op_sel:[0,1,0]
	v_pk_fma_f32 v[26:27], v[130:131], v[90:91], v[26:27] op_sel:[0,1,0]
	v_pk_fma_f32 v[36:37], v[132:133], v[92:93], v[36:37] op_sel_hi:[1,0,1]
	v_pk_fma_f32 v[34:35], v[130:131], v[92:93], v[34:35] op_sel_hi:[1,0,1]
	v_pk_fma_f32 v[4:5], v[132:133], v[170:171], v[4:5] op_sel_hi:[1,0,1]
	v_pk_fma_f32 v[2:3], v[130:131], v[170:171], v[2:3] op_sel_hi:[1,0,1]
	v_pk_fma_f32 v[24:25], v[132:133], v[172:173], v[24:25] op_sel_hi:[1,0,1]
	v_pk_fma_f32 v[22:23], v[130:131], v[172:173], v[22:23] op_sel_hi:[1,0,1]
	v_pk_fma_f32 v[32:33], v[132:133], v[150:151], v[32:33] op_sel_hi:[1,0,1]
	v_pk_fma_f32 v[30:31], v[130:131], v[150:151], v[30:31] op_sel_hi:[1,0,1]
	v_lshl_add_u64 v[130:131], v[46:47], 0, s[100:101]
	s_add_u32 s100, s100, 0xc000
	global_load_dwordx4 v[130:133], v[130:131], off
	s_nop 0
	s_waitcnt vmcnt(7)
	v_pk_fma_f32 v[8:9], v[136:137], v[94:95], v[8:9] op_sel_hi:[1,0,1]
	v_pk_fma_f32 v[6:7], v[134:135], v[94:95], v[6:7] op_sel_hi:[1,0,1]
	v_pk_fma_f32 v[12:13], v[136:137], v[94:95], v[12:13] op_sel:[0,1,0]
	v_pk_fma_f32 v[10:11], v[134:135], v[94:95], v[10:11] op_sel:[0,1,0]
	v_pk_fma_f32 v[16:17], v[136:137], v[96:97], v[16:17] op_sel_hi:[1,0,1]
	v_pk_fma_f32 v[14:15], v[134:135], v[96:97], v[14:15] op_sel_hi:[1,0,1]
	v_pk_fma_f32 v[4:5], v[136:137], v[174:175], v[4:5] op_sel_hi:[1,0,1]
	v_pk_fma_f32 v[2:3], v[134:135], v[174:175], v[2:3] op_sel_hi:[1,0,1]
	v_pk_fma_f32 v[20:21], v[136:137], v[98:99], v[20:21] op_sel_hi:[1,0,1]
	v_pk_fma_f32 v[18:19], v[134:135], v[98:99], v[18:19] op_sel_hi:[1,0,1]
	v_pk_fma_f32 v[28:29], v[136:137], v[98:99], v[28:29] op_sel:[0,1,0]
	v_pk_fma_f32 v[26:27], v[134:135], v[98:99], v[26:27] op_sel:[0,1,0]
	v_pk_fma_f32 v[36:37], v[136:137], v[100:101], v[36:37] op_sel_hi:[1,0,1]
	v_pk_fma_f32 v[34:35], v[134:135], v[100:101], v[34:35] op_sel_hi:[1,0,1]
	v_pk_fma_f32 v[24:25], v[136:137], v[176:177], v[24:25] op_sel_hi:[1,0,1]
	v_pk_fma_f32 v[22:23], v[134:135], v[176:177], v[22:23] op_sel_hi:[1,0,1]
	v_pk_fma_f32 v[32:33], v[136:137], v[178:179], v[32:33] op_sel_hi:[1,0,1]
	v_pk_fma_f32 v[30:31], v[134:135], v[178:179], v[30:31] op_sel_hi:[1,0,1]
	v_lshl_add_u64 v[134:135], v[46:47], 0, s[100:101]
	s_add_u32 s100, s100, 0xc000
	global_load_dwordx4 v[134:137], v[134:135], off
	s_nop 0
	s_waitcnt vmcnt(7)
	v_pk_fma_f32 v[8:9], v[140:141], v[102:103], v[8:9] op_sel_hi:[1,0,1]
	v_pk_fma_f32 v[6:7], v[138:139], v[102:103], v[6:7] op_sel_hi:[1,0,1]
	v_pk_fma_f32 v[12:13], v[140:141], v[102:103], v[12:13] op_sel:[0,1,0]
	v_pk_fma_f32 v[10:11], v[138:139], v[102:103], v[10:11] op_sel:[0,1,0]
	v_pk_fma_f32 v[16:17], v[140:141], v[104:105], v[16:17] op_sel_hi:[1,0,1]
	v_pk_fma_f32 v[14:15], v[138:139], v[104:105], v[14:15] op_sel_hi:[1,0,1]
	v_pk_fma_f32 v[20:21], v[140:141], v[106:107], v[20:21] op_sel_hi:[1,0,1]
	v_pk_fma_f32 v[18:19], v[138:139], v[106:107], v[18:19] op_sel_hi:[1,0,1]
	v_pk_fma_f32 v[28:29], v[140:141], v[106:107], v[28:29] op_sel:[0,1,0]
	v_pk_fma_f32 v[26:27], v[138:139], v[106:107], v[26:27] op_sel:[0,1,0]
	v_pk_fma_f32 v[36:37], v[140:141], v[108:109], v[36:37] op_sel_hi:[1,0,1]
	v_pk_fma_f32 v[34:35], v[138:139], v[108:109], v[34:35] op_sel_hi:[1,0,1]
	v_pk_fma_f32 v[4:5], v[140:141], v[180:181], v[4:5] op_sel_hi:[1,0,1]
	v_pk_fma_f32 v[2:3], v[138:139], v[180:181], v[2:3] op_sel_hi:[1,0,1]
	v_pk_fma_f32 v[24:25], v[140:141], v[182:183], v[24:25] op_sel_hi:[1,0,1]
	v_pk_fma_f32 v[22:23], v[138:139], v[182:183], v[22:23] op_sel_hi:[1,0,1]
	v_pk_fma_f32 v[32:33], v[140:141], v[152:153], v[32:33] op_sel_hi:[1,0,1]
	v_pk_fma_f32 v[30:31], v[138:139], v[152:153], v[30:31] op_sel_hi:[1,0,1]
	v_lshl_add_u64 v[138:139], v[46:47], 0, s[100:101]
	s_add_u32 s100, s100, 0xc000
	global_load_dwordx4 v[138:141], v[138:139], off
	s_nop 0
	s_waitcnt vmcnt(7)
	v_pk_fma_f32 v[8:9], v[144:145], v[110:111], v[8:9] op_sel_hi:[1,0,1]
	v_pk_fma_f32 v[6:7], v[142:143], v[110:111], v[6:7] op_sel_hi:[1,0,1]
	v_pk_fma_f32 v[12:13], v[144:145], v[110:111], v[12:13] op_sel:[0,1,0]
	v_pk_fma_f32 v[10:11], v[142:143], v[110:111], v[10:11] op_sel:[0,1,0]
	v_pk_fma_f32 v[16:17], v[144:145], v[112:113], v[16:17] op_sel_hi:[1,0,1]
	v_pk_fma_f32 v[14:15], v[142:143], v[112:113], v[14:15] op_sel_hi:[1,0,1]
	v_pk_fma_f32 v[4:5], v[144:145], v[184:185], v[4:5] op_sel_hi:[1,0,1]
	v_pk_fma_f32 v[2:3], v[142:143], v[184:185], v[2:3] op_sel_hi:[1,0,1]
	v_pk_fma_f32 v[20:21], v[144:145], v[114:115], v[20:21] op_sel_hi:[1,0,1]
	v_pk_fma_f32 v[18:19], v[142:143], v[114:115], v[18:19] op_sel_hi:[1,0,1]
	v_pk_fma_f32 v[28:29], v[144:145], v[114:115], v[28:29] op_sel:[0,1,0]
	v_pk_fma_f32 v[26:27], v[142:143], v[114:115], v[26:27] op_sel:[0,1,0]
	v_pk_fma_f32 v[36:37], v[144:145], v[116:117], v[36:37] op_sel_hi:[1,0,1]
	v_pk_fma_f32 v[34:35], v[142:143], v[116:117], v[34:35] op_sel_hi:[1,0,1]
	v_pk_fma_f32 v[24:25], v[144:145], v[186:187], v[24:25] op_sel_hi:[1,0,1]
	v_pk_fma_f32 v[22:23], v[142:143], v[186:187], v[22:23] op_sel_hi:[1,0,1]
	v_pk_fma_f32 v[32:33], v[144:145], v[188:189], v[32:33] op_sel_hi:[1,0,1]
	v_pk_fma_f32 v[30:31], v[142:143], v[188:189], v[30:31] op_sel_hi:[1,0,1]
	v_lshl_add_u64 v[142:143], v[46:47], 0, s[100:101]
	s_add_u32 s100, s100, 0xc000
	global_load_dwordx4 v[142:145], v[142:143], off
	s_nop 0
	s_cmp_eq_u32 s6, 0xc00000
	s_cbranch_scc0 .LBB0_22
	s_waitcnt vmcnt(0)
	s_add_i32 s6, s41, s0
	s_mul_i32 s6, s6, 9
	v_lshl_add_u64 v[46:47], s[4:5], 2, v[42:43]
	v_mad_i64_i32 v[48:49], s[4:5], s6, v1, v[46:47]
	s_add_i32 s4, s6, 1
	global_store_dwordx4 v[48:49], v[6:9], off
	s_nop 1
	v_mad_i64_i32 v[6:7], s[4:5], s4, v1, v[46:47]
	s_add_i32 s4, s6, 2
	global_store_dwordx4 v[6:7], v[10:13], off
	v_mad_i64_i32 v[6:7], s[4:5], s4, v1, v[46:47]
	s_add_i32 s4, s6, 3
	global_store_dwordx4 v[6:7], v[14:17], off
	v_mad_i64_i32 v[6:7], s[4:5], s4, v1, v[46:47]
	s_add_i32 s4, s6, 4
	global_store_dwordx4 v[6:7], v[2:5], off
	s_nop 1
	v_mad_i64_i32 v[2:3], s[4:5], s4, v1, v[46:47]
	s_add_i32 s4, s6, 5
	global_store_dwordx4 v[2:3], v[18:21], off
	v_mad_i64_i32 v[2:3], s[4:5], s4, v1, v[46:47]
	s_add_i32 s4, s6, 6
	global_store_dwordx4 v[2:3], v[26:29], off
	v_mad_i64_i32 v[2:3], s[4:5], s4, v1, v[46:47]
	s_add_i32 s4, s6, 7
	global_store_dwordx4 v[2:3], v[34:37], off
	v_mad_i64_i32 v[2:3], s[4:5], s4, v1, v[46:47]
	s_add_i32 s6, s6, 8
	global_store_dwordx4 v[2:3], v[22:25], off
	v_mad_i64_i32 v[2:3], s[4:5], s6, v1, v[46:47]
	s_add_i32 s4, s39, 0x800
	s_cmpk_gt_i32 s39, 0xfdff
	s_mov_b32 s39, s4
	global_store_dwordx4 v[2:3], v[30:33], off
	s_cbranch_scc0 .LBB0_21

	.amdhsa_kernel _Z6mk_fwd6MkArgs
		.amdhsa_group_segment_fixed_size 0
		.amdhsa_private_segment_fixed_size 0
		.amdhsa_kernarg_size 456
		.amdhsa_user_sgpr_count 2
		.amdhsa_user_sgpr_dispatch_ptr 0
		.amdhsa_user_sgpr_queue_ptr 0
		.amdhsa_user_sgpr_kernarg_segment_ptr 1
		.amdhsa_user_sgpr_dispatch_id 0
		.amdhsa_user_sgpr_kernarg_preload_length 0
		.amdhsa_user_sgpr_kernarg_preload_offset 0
		.amdhsa_user_sgpr_private_segment_size 0
		.amdhsa_uses_dynamic_stack 0
		.amdhsa_enable_private_segment 0
		.amdhsa_system_sgpr_workgroup_id_x 1
		.amdhsa_system_sgpr_workgroup_id_y 0
		.amdhsa_system_sgpr_workgroup_id_z 0
		.amdhsa_system_sgpr_workgroup_info 0
		.amdhsa_system_vgpr_workitem_id 0
		.amdhsa_next_free_vgpr 256
		.amdhsa_next_free_sgpr 102
		.amdhsa_accum_offset 256
		.amdhsa_reserve_vcc 1
		.amdhsa_float_round_mode_32 0
		.amdhsa_float_round_mode_16_64 0
		.amdhsa_float_denorm_mode_32 3
		.amdhsa_float_denorm_mode_16_64 3
		.amdhsa_dx10_clamp 1
		.amdhsa_ieee_mode 1
		.amdhsa_fp16_overflow 0
		.amdhsa_tg_split 0
		.amdhsa_exception_fp_ieee_invalid_op 0
		.amdhsa_exception_fp_denorm_src 0
		.amdhsa_exception_fp_ieee_div_zero 0
		.amdhsa_exception_fp_ieee_overflow 0
		.amdhsa_exception_fp_ieee_underflow 0
		.amdhsa_exception_fp_ieee_inexact 0
		.amdhsa_exception_int_div_zero 0
	.end_amdhsa_kernel

amdhsa.kernels:
  - .agpr_count:     0
    .args:
      - .offset:         0
        .size:           200
        .value_kind:     by_value
      - .offset:         200
        .size:           4
        .value_kind:     hidden_block_count_x
      - .offset:         204
        .size:           4
        .value_kind:     hidden_block_count_y
      - .offset:         208
        .size:           4
        .value_kind:     hidden_block_count_z
      - .offset:         212
        .size:           2
        .value_kind:     hidden_group_size_x
      - .offset:         214
        .size:           2
        .value_kind:     hidden_group_size_y
      - .offset:         216
        .size:           2
        .value_kind:     hidden_group_size_z
      - .offset:         218
        .size:           2
        .value_kind:     hidden_remainder_x
      - .offset:         220
        .size:           2
        .value_kind:     hidden_remainder_y
      - .offset:         222
        .size:           2
        .value_kind:     hidden_remainder_z
      - .offset:         240
        .size:           8
        .value_kind:     hidden_global_offset_x
      - .offset:         248
        .size:           8
        .value_kind:     hidden_global_offset_y
      - .offset:         256
        .size:           8
        .value_kind:     hidden_global_offset_z
      - .offset:         264
        .size:           2
        .value_kind:     hidden_grid_dims
      - .offset:         320
        .size:           4
        .value_kind:     hidden_dynamic_lds_size
    .group_segment_fixed_size: 0
    .kernarg_segment_align: 8
    .kernarg_segment_size: 456
    .language:       OpenCL C
    .language_version:
      - 2
      - 0
    .max_flat_workgroup_size: 512
    .name:           _Z6mk_fwd6MkArgs
    .private_segment_fixed_size: 0
    .sgpr_count:     108
    .sgpr_spill_count: 113
    .symbol:         _Z6mk_fwd6MkArgs.kd
    .uniform_work_group_size: 1
    .uses_dynamic_stack: false
    .vgpr_count:     256
    .vgpr_spill_count: 0
    .wavefront_size: 64
